# MoBA softmax row-max exchange across the four lane groups via v_permlane16_swap / v_permlane32_swap instead of two ds_bpermute shuffles
# speedup vs baseline: 1.0058x; 1.0029x over previous
; __device__ void moba_item(const P& p, int bh, int qt, char* smem) {
;     ...
;       mx = fmaxf(mx, __shfl_xor(mx, 16));
;       mx = fmaxf(mx, __shfl_xor(mx, 32));
;       const float mnew = (mx > mrun + 6.f) ? mx : mrun;
;       const float muse = (mnew == -INFINITY) ? 0.f : mnew;
;       const bool resc = __any(mnew != mrun);
;       const float alpha = __builtin_amdgcn_exp2f(mrun - muse);
.LBB0_622:
	s_mov_b32 s0, 0xff800000
	v_max_f32_e32 v132, v0, v0
	v_max_f32_e32 v133, v0, v0
	s_nop 1
	v_permlane16_swap_b32_e32 v132, v133
	s_nop 0
	v_max_f32_e32 v0, v132, v133
	v_mov_b32_e32 v132, v0
	v_mov_b32_e32 v133, v0
	s_nop 1
	v_permlane32_swap_b32_e32 v132, v133
	s_nop 0
	v_max_f32_e32 v0, v132, v133
	v_add_f32_e32 v132, 0x40c00000, v189
	v_cmp_gt_f32_e32 vcc, v0, v132
	s_nop 1
	v_cndmask_b32_e32 v190, v189, v0, vcc
	v_cmp_neq_f32_e32 vcc, s0, v190
	s_nop 1
	v_cndmask_b32_e32 v132, 0, v190, vcc
	v_sub_f32_e32 v0, v189, v132
	v_exp_f32_e32 v0, v0
	v_cmp_neq_f32_e32 vcc, v190, v189
	s_cbranch_vccz .LBB0_624
	v_pk_mul_f32 v[110:111], v[110:111], v[0:1] op_sel_hi:[1,0]
	v_pk_mul_f32 v[108:109], v[108:109], v[0:1] op_sel_hi:[1,0]
	v_pk_mul_f32 v[114:115], v[114:115], v[0:1] op_sel_hi:[1,0]
	v_pk_mul_f32 v[112:113], v[112:113], v[0:1] op_sel_hi:[1,0]
	v_pk_mul_f32 v[70:71], v[70:71], v[0:1] op_sel_hi:[1,0]
	v_pk_mul_f32 v[68:69], v[68:69], v[0:1] op_sel_hi:[1,0]
	v_pk_mul_f32 v[78:79], v[78:79], v[0:1] op_sel_hi:[1,0]
	v_pk_mul_f32 v[76:77], v[76:77], v[0:1] op_sel_hi:[1,0]
	v_pk_mul_f32 v[62:63], v[62:63], v[0:1] op_sel_hi:[1,0]
	v_pk_mul_f32 v[60:61], v[60:61], v[0:1] op_sel_hi:[1,0]
	v_pk_mul_f32 v[74:75], v[74:75], v[0:1] op_sel_hi:[1,0]
	v_pk_mul_f32 v[72:73], v[72:73], v[0:1] op_sel_hi:[1,0]
	v_pk_mul_f32 v[54:55], v[54:55], v[0:1] op_sel_hi:[1,0]
	v_pk_mul_f32 v[52:53], v[52:53], v[0:1] op_sel_hi:[1,0]
	v_pk_mul_f32 v[106:107], v[106:107], v[0:1] op_sel_hi:[1,0]
	v_pk_mul_f32 v[104:105], v[104:105], v[0:1] op_sel_hi:[1,0]

; __device__ void moba_item(const P& p, int bh, int qt, char* smem) {
;     ...
;       mx = fmaxf(mx, __shfl_xor(mx, 16));
;       mx = fmaxf(mx, __shfl_xor(mx, 32));
;       const float mnew = (mx > mrun + 6.f) ? mx : mrun;
;       const float muse = (mnew == -INFINITY) ? 0.f : mnew;
;       const bool resc = __any(mnew != mrun);
;       const float alpha = __builtin_amdgcn_exp2f(mrun - muse);
.LBB0_634:
	s_mov_b32 s0, 0xff800000
	v_max_f32_e32 v132, v189, v189
	v_max_f32_e32 v133, v189, v189
	s_nop 1
	v_permlane16_swap_b32_e32 v132, v133
	s_nop 0
	v_max_f32_e32 v0, v132, v133
	v_mov_b32_e32 v132, v0
	v_mov_b32_e32 v133, v0
	s_nop 1
	v_permlane32_swap_b32_e32 v132, v133
	s_nop 0
	v_max_f32_e32 v0, v132, v133
	v_add_f32_e32 v132, 0x40c00000, v190
	v_cmp_gt_f32_e32 vcc, v0, v132
	s_nop 1
	v_cndmask_b32_e32 v189, v190, v0, vcc
	v_cmp_neq_f32_e32 vcc, s0, v189
	s_nop 1
	v_cndmask_b32_e32 v132, 0, v189, vcc
	v_sub_f32_e32 v0, v190, v132
	v_exp_f32_e32 v0, v0
	v_cmp_neq_f32_e32 vcc, v189, v190
	s_cbranch_vccz .LBB0_636
	v_pk_mul_f32 v[110:111], v[110:111], v[0:1] op_sel_hi:[1,0]
	v_pk_mul_f32 v[108:109], v[108:109], v[0:1] op_sel_hi:[1,0]
	v_pk_mul_f32 v[114:115], v[114:115], v[0:1] op_sel_hi:[1,0]
	v_pk_mul_f32 v[112:113], v[112:113], v[0:1] op_sel_hi:[1,0]
	v_pk_mul_f32 v[70:71], v[70:71], v[0:1] op_sel_hi:[1,0]
	v_pk_mul_f32 v[68:69], v[68:69], v[0:1] op_sel_hi:[1,0]
	v_pk_mul_f32 v[78:79], v[78:79], v[0:1] op_sel_hi:[1,0]
	v_pk_mul_f32 v[76:77], v[76:77], v[0:1] op_sel_hi:[1,0]
	v_pk_mul_f32 v[62:63], v[62:63], v[0:1] op_sel_hi:[1,0]
	v_pk_mul_f32 v[60:61], v[60:61], v[0:1] op_sel_hi:[1,0]
	v_pk_mul_f32 v[74:75], v[74:75], v[0:1] op_sel_hi:[1,0]
	v_pk_mul_f32 v[72:73], v[72:73], v[0:1] op_sel_hi:[1,0]
	v_pk_mul_f32 v[54:55], v[54:55], v[0:1] op_sel_hi:[1,0]
	v_pk_mul_f32 v[52:53], v[52:53], v[0:1] op_sel_hi:[1,0]
	v_pk_mul_f32 v[106:107], v[106:107], v[0:1] op_sel_hi:[1,0]
	v_pk_mul_f32 v[104:105], v[104:105], v[0:1] op_sel_hi:[1,0]
